# branch GEMM K-seams run at equal wave priority (static raise dropped at seam entry, restored for waves 4-7 at seam exit)
# speedup vs baseline: 1.0079x; 1.0059x over previous
.LBB0_214:
	s_setprio 0
	s_cmpk_eq_i32 s50, 0x400
	s_cselect_b32 s1, 0, 0x400
	v_add_u32_e32 v172, s1, v171
	v_add_lshl_u32 v172, v172, v170, 1
	global_load_dwordx4 v[132:135], v172, s[4:5]
	global_load_dwordx4 v[136:139], v172, s[4:5] offset:2048
	global_load_dwordx4 v[190:193], v172, s[4:5] offset:256
	global_load_dwordx4 v[194:197], v172, s[4:5] offset:2304
	v_add_u32_e32 v172, 0x26000, v172
	global_load_dwordx4 v[198:201], v172, s[4:5]
	global_load_dwordx4 v[202:205], v172, s[4:5] offset:2048
	global_load_dwordx4 v[206:209], v172, s[4:5] offset:256
	global_load_dwordx4 v[210:213], v172, s[4:5] offset:2304
	v_add_u32_e32 v172, 0x26000, v172
	global_load_dwordx4 v[214:217], v172, s[4:5]
	global_load_dwordx4 v[218:221], v172, s[4:5] offset:2048
	global_load_dwordx4 v[222:225], v172, s[4:5] offset:256
	global_load_dwordx4 v[226:229], v172, s[4:5] offset:2304
	v_add_u32_e32 v172, 0x26000, v172
	global_load_dwordx4 v[230:233], v172, s[4:5]
	global_load_dwordx4 v[234:237], v172, s[4:5] offset:2048
	global_load_dwordx4 v[238:241], v172, s[4:5] offset:256
	global_load_dwordx4 v[242:245], v172, s[4:5] offset:2304
	s_waitcnt vmcnt(14)
	v_lshlrev_b32_e32 v250, 16, v136
	v_and_b32_e32 v251, 0xffff0000, v136
	v_rcp_f32_e32 v250, v250
	v_rcp_f32_e32 v251, v251
	v_lshlrev_b32_e32 v248, 16, v132
	v_and_b32_e32 v249, 0xffff0000, v132
	v_pk_mul_f32 v[250:251], v[250:251], v[248:249]
	v_pk_mul_f32 v[128:129], v[128:129], v[250:251]
	v_lshlrev_b32_e32 v246, 16, v137
	v_and_b32_e32 v247, 0xffff0000, v137
	v_rcp_f32_e32 v246, v246
	v_rcp_f32_e32 v247, v247
	v_lshlrev_b32_e32 v174, 16, v133
	v_and_b32_e32 v175, 0xffff0000, v133
	v_pk_mul_f32 v[246:247], v[246:247], v[174:175]
	v_pk_mul_f32 v[130:131], v[130:131], v[246:247]
	v_lshlrev_b32_e32 v250, 16, v138
	v_and_b32_e32 v251, 0xffff0000, v138
	v_rcp_f32_e32 v250, v250
	v_rcp_f32_e32 v251, v251
	v_lshlrev_b32_e32 v248, 16, v134
	v_and_b32_e32 v249, 0xffff0000, v134
	v_pk_mul_f32 v[250:251], v[250:251], v[248:249]
	v_pk_mul_f32 v[124:125], v[124:125], v[250:251]
	v_lshlrev_b32_e32 v246, 16, v139
	v_and_b32_e32 v247, 0xffff0000, v139
	v_rcp_f32_e32 v246, v246
	v_rcp_f32_e32 v247, v247
	v_lshlrev_b32_e32 v174, 16, v135
	v_and_b32_e32 v175, 0xffff0000, v135
	v_pk_mul_f32 v[246:247], v[246:247], v[174:175]
	v_pk_mul_f32 v[126:127], v[126:127], v[246:247]
	v_add_u32_e32 v172, 0xbe000, v172
	global_load_dwordx4 v[132:135], v172, s[4:5]
	global_load_dwordx4 v[136:139], v172, s[4:5] offset:2048
	s_waitcnt vmcnt(14)
	v_lshlrev_b32_e32 v250, 16, v194
	v_and_b32_e32 v251, 0xffff0000, v194
	v_rcp_f32_e32 v250, v250
	v_rcp_f32_e32 v251, v251
	v_lshlrev_b32_e32 v248, 16, v190
	v_and_b32_e32 v249, 0xffff0000, v190
	v_pk_mul_f32 v[250:251], v[250:251], v[248:249]
	v_pk_mul_f32 v[120:121], v[120:121], v[250:251]
	v_lshlrev_b32_e32 v246, 16, v195
	v_and_b32_e32 v247, 0xffff0000, v195
	v_rcp_f32_e32 v246, v246
	v_rcp_f32_e32 v247, v247
	v_lshlrev_b32_e32 v174, 16, v191
	v_and_b32_e32 v175, 0xffff0000, v191
	v_pk_mul_f32 v[246:247], v[246:247], v[174:175]
	v_pk_mul_f32 v[122:123], v[122:123], v[246:247]
	v_lshlrev_b32_e32 v250, 16, v196
	v_and_b32_e32 v251, 0xffff0000, v196
	v_rcp_f32_e32 v250, v250
	v_rcp_f32_e32 v251, v251
	v_lshlrev_b32_e32 v248, 16, v192
	v_and_b32_e32 v249, 0xffff0000, v192
	v_pk_mul_f32 v[250:251], v[250:251], v[248:249]
	v_pk_mul_f32 v[116:117], v[116:117], v[250:251]
	v_lshlrev_b32_e32 v246, 16, v197
	v_and_b32_e32 v247, 0xffff0000, v197
	v_rcp_f32_e32 v246, v246
	v_rcp_f32_e32 v247, v247
	v_lshlrev_b32_e32 v174, 16, v193
	v_and_b32_e32 v175, 0xffff0000, v193
	v_pk_mul_f32 v[246:247], v[246:247], v[174:175]
	v_pk_mul_f32 v[118:119], v[118:119], v[246:247]
	global_load_dwordx4 v[190:193], v172, s[4:5] offset:256
	global_load_dwordx4 v[194:197], v172, s[4:5] offset:2304
	s_waitcnt vmcnt(14)
	v_lshlrev_b32_e32 v250, 16, v202
	v_and_b32_e32 v251, 0xffff0000, v202
	v_rcp_f32_e32 v250, v250
	v_rcp_f32_e32 v251, v251
	v_lshlrev_b32_e32 v248, 16, v198
	v_and_b32_e32 v249, 0xffff0000, v198
	v_pk_mul_f32 v[250:251], v[250:251], v[248:249]
	v_pk_mul_f32 v[112:113], v[112:113], v[250:251]
	v_lshlrev_b32_e32 v246, 16, v203
	v_and_b32_e32 v247, 0xffff0000, v203
	v_rcp_f32_e32 v246, v246
	v_rcp_f32_e32 v247, v247
	v_lshlrev_b32_e32 v174, 16, v199
	v_and_b32_e32 v175, 0xffff0000, v199
	v_pk_mul_f32 v[246:247], v[246:247], v[174:175]
	v_pk_mul_f32 v[114:115], v[114:115], v[246:247]
	v_lshlrev_b32_e32 v250, 16, v204
	v_and_b32_e32 v251, 0xffff0000, v204
	v_rcp_f32_e32 v250, v250
	v_rcp_f32_e32 v251, v251
	v_lshlrev_b32_e32 v248, 16, v200
	v_and_b32_e32 v249, 0xffff0000, v200
	v_pk_mul_f32 v[250:251], v[250:251], v[248:249]
	v_pk_mul_f32 v[108:109], v[108:109], v[250:251]
	v_lshlrev_b32_e32 v246, 16, v205
	v_and_b32_e32 v247, 0xffff0000, v205
	v_rcp_f32_e32 v246, v246
	v_rcp_f32_e32 v247, v247
	v_lshlrev_b32_e32 v174, 16, v201
	v_and_b32_e32 v175, 0xffff0000, v201
	v_pk_mul_f32 v[246:247], v[246:247], v[174:175]
	v_pk_mul_f32 v[110:111], v[110:111], v[246:247]
	v_add_u32_e32 v172, 0x26000, v172
	global_load_dwordx4 v[198:201], v172, s[4:5]
	global_load_dwordx4 v[202:205], v172, s[4:5] offset:2048
	s_waitcnt vmcnt(14)
	v_lshlrev_b32_e32 v250, 16, v210
	v_and_b32_e32 v251, 0xffff0000, v210
	v_rcp_f32_e32 v250, v250
	v_rcp_f32_e32 v251, v251
	v_lshlrev_b32_e32 v248, 16, v206
	v_and_b32_e32 v249, 0xffff0000, v206
	v_pk_mul_f32 v[250:251], v[250:251], v[248:249]
	v_pk_mul_f32 v[104:105], v[104:105], v[250:251]
	v_lshlrev_b32_e32 v246, 16, v211
	v_and_b32_e32 v247, 0xffff0000, v211
	v_rcp_f32_e32 v246, v246
	v_rcp_f32_e32 v247, v247
	v_lshlrev_b32_e32 v174, 16, v207
	v_and_b32_e32 v175, 0xffff0000, v207
	v_pk_mul_f32 v[246:247], v[246:247], v[174:175]
	v_pk_mul_f32 v[106:107], v[106:107], v[246:247]
	v_lshlrev_b32_e32 v250, 16, v212
	v_and_b32_e32 v251, 0xffff0000, v212
	v_rcp_f32_e32 v250, v250
	v_rcp_f32_e32 v251, v251
	v_lshlrev_b32_e32 v248, 16, v208
	v_and_b32_e32 v249, 0xffff0000, v208
	v_pk_mul_f32 v[250:251], v[250:251], v[248:249]
	v_pk_mul_f32 v[100:101], v[100:101], v[250:251]
	v_lshlrev_b32_e32 v246, 16, v213
	v_and_b32_e32 v247, 0xffff0000, v213
	v_rcp_f32_e32 v246, v246
	v_rcp_f32_e32 v247, v247
	v_lshlrev_b32_e32 v174, 16, v209
	v_and_b32_e32 v175, 0xffff0000, v209
	v_pk_mul_f32 v[246:247], v[246:247], v[174:175]
	v_pk_mul_f32 v[102:103], v[102:103], v[246:247]
	global_load_dwordx4 v[206:209], v172, s[4:5] offset:256
	global_load_dwordx4 v[210:213], v172, s[4:5] offset:2304
	s_waitcnt vmcnt(14)
	v_lshlrev_b32_e32 v250, 16, v218
	v_and_b32_e32 v251, 0xffff0000, v218
	v_rcp_f32_e32 v250, v250
	v_rcp_f32_e32 v251, v251
	v_lshlrev_b32_e32 v248, 16, v214
	v_and_b32_e32 v249, 0xffff0000, v214
	v_pk_mul_f32 v[250:251], v[250:251], v[248:249]
	v_pk_mul_f32 v[96:97], v[96:97], v[250:251]
	v_lshlrev_b32_e32 v246, 16, v219
	v_and_b32_e32 v247, 0xffff0000, v219
	v_rcp_f32_e32 v246, v246
	v_rcp_f32_e32 v247, v247
	v_lshlrev_b32_e32 v174, 16, v215
	v_and_b32_e32 v175, 0xffff0000, v215
	v_pk_mul_f32 v[246:247], v[246:247], v[174:175]
	v_pk_mul_f32 v[98:99], v[98:99], v[246:247]
	v_lshlrev_b32_e32 v250, 16, v220
	v_and_b32_e32 v251, 0xffff0000, v220
	v_rcp_f32_e32 v250, v250
	v_rcp_f32_e32 v251, v251
	v_lshlrev_b32_e32 v248, 16, v216
	v_and_b32_e32 v249, 0xffff0000, v216
	v_pk_mul_f32 v[250:251], v[250:251], v[248:249]
	v_pk_mul_f32 v[92:93], v[92:93], v[250:251]
	v_lshlrev_b32_e32 v246, 16, v221
	v_and_b32_e32 v247, 0xffff0000, v221
	v_rcp_f32_e32 v246, v246
	v_rcp_f32_e32 v247, v247
	v_lshlrev_b32_e32 v174, 16, v217
	v_and_b32_e32 v175, 0xffff0000, v217
	v_pk_mul_f32 v[246:247], v[246:247], v[174:175]
	v_pk_mul_f32 v[94:95], v[94:95], v[246:247]
	v_add_u32_e32 v172, 0x26000, v172
	global_load_dwordx4 v[214:217], v172, s[4:5]
	global_load_dwordx4 v[218:221], v172, s[4:5] offset:2048
	s_waitcnt vmcnt(14)
	v_lshlrev_b32_e32 v250, 16, v226
	v_and_b32_e32 v251, 0xffff0000, v226
	v_rcp_f32_e32 v250, v250
	v_rcp_f32_e32 v251, v251
	v_lshlrev_b32_e32 v248, 16, v222
	v_and_b32_e32 v249, 0xffff0000, v222
	v_pk_mul_f32 v[250:251], v[250:251], v[248:249]
	v_pk_mul_f32 v[88:89], v[88:89], v[250:251]
	v_lshlrev_b32_e32 v246, 16, v227
	v_and_b32_e32 v247, 0xffff0000, v227
	v_rcp_f32_e32 v246, v246
	v_rcp_f32_e32 v247, v247
	v_lshlrev_b32_e32 v174, 16, v223
	v_and_b32_e32 v175, 0xffff0000, v223
	v_pk_mul_f32 v[246:247], v[246:247], v[174:175]
	v_pk_mul_f32 v[90:91], v[90:91], v[246:247]
	v_lshlrev_b32_e32 v250, 16, v228
	v_and_b32_e32 v251, 0xffff0000, v228
	v_rcp_f32_e32 v250, v250
	v_rcp_f32_e32 v251, v251
	v_lshlrev_b32_e32 v248, 16, v224
	v_and_b32_e32 v249, 0xffff0000, v224
	v_pk_mul_f32 v[250:251], v[250:251], v[248:249]
	v_pk_mul_f32 v[84:85], v[84:85], v[250:251]
	v_lshlrev_b32_e32 v246, 16, v229
	v_and_b32_e32 v247, 0xffff0000, v229
	v_rcp_f32_e32 v246, v246
	v_rcp_f32_e32 v247, v247
	v_lshlrev_b32_e32 v174, 16, v225
	v_and_b32_e32 v175, 0xffff0000, v225
	v_pk_mul_f32 v[246:247], v[246:247], v[174:175]
	v_pk_mul_f32 v[86:87], v[86:87], v[246:247]
	global_load_dwordx4 v[222:225], v172, s[4:5] offset:256
	global_load_dwordx4 v[226:229], v172, s[4:5] offset:2304
	s_waitcnt vmcnt(14)
	v_lshlrev_b32_e32 v250, 16, v234
	v_and_b32_e32 v251, 0xffff0000, v234
	v_rcp_f32_e32 v250, v250
	v_rcp_f32_e32 v251, v251
	v_lshlrev_b32_e32 v248, 16, v230
	v_and_b32_e32 v249, 0xffff0000, v230
	v_pk_mul_f32 v[250:251], v[250:251], v[248:249]
	v_pk_mul_f32 v[80:81], v[80:81], v[250:251]
	v_lshlrev_b32_e32 v246, 16, v235
	v_and_b32_e32 v247, 0xffff0000, v235
	v_rcp_f32_e32 v246, v246
	v_rcp_f32_e32 v247, v247
	v_lshlrev_b32_e32 v174, 16, v231
	v_and_b32_e32 v175, 0xffff0000, v231
	v_pk_mul_f32 v[246:247], v[246:247], v[174:175]
	v_pk_mul_f32 v[82:83], v[82:83], v[246:247]
	v_lshlrev_b32_e32 v250, 16, v236
	v_and_b32_e32 v251, 0xffff0000, v236
	v_rcp_f32_e32 v250, v250
	v_rcp_f32_e32 v251, v251
	v_lshlrev_b32_e32 v248, 16, v232
	v_and_b32_e32 v249, 0xffff0000, v232
	v_pk_mul_f32 v[250:251], v[250:251], v[248:249]
	v_pk_mul_f32 v[76:77], v[76:77], v[250:251]
	v_lshlrev_b32_e32 v246, 16, v237
	v_and_b32_e32 v247, 0xffff0000, v237
	v_rcp_f32_e32 v246, v246
	v_rcp_f32_e32 v247, v247
	v_lshlrev_b32_e32 v174, 16, v233
	v_and_b32_e32 v175, 0xffff0000, v233
	v_pk_mul_f32 v[246:247], v[246:247], v[174:175]
	v_pk_mul_f32 v[78:79], v[78:79], v[246:247]
	v_add_u32_e32 v172, 0x26000, v172
	global_load_dwordx4 v[230:233], v172, s[4:5]
	global_load_dwordx4 v[234:237], v172, s[4:5] offset:2048
	s_waitcnt vmcnt(14)
	v_lshlrev_b32_e32 v250, 16, v242
	v_and_b32_e32 v251, 0xffff0000, v242
	v_rcp_f32_e32 v250, v250
	v_rcp_f32_e32 v251, v251
	v_lshlrev_b32_e32 v248, 16, v238
	v_and_b32_e32 v249, 0xffff0000, v238
	v_pk_mul_f32 v[250:251], v[250:251], v[248:249]
	v_pk_mul_f32 v[72:73], v[72:73], v[250:251]
	v_lshlrev_b32_e32 v246, 16, v243
	v_and_b32_e32 v247, 0xffff0000, v243
	v_rcp_f32_e32 v246, v246
	v_rcp_f32_e32 v247, v247
	v_lshlrev_b32_e32 v174, 16, v239
	v_and_b32_e32 v175, 0xffff0000, v239
	v_pk_mul_f32 v[246:247], v[246:247], v[174:175]
	v_pk_mul_f32 v[74:75], v[74:75], v[246:247]
	v_lshlrev_b32_e32 v250, 16, v244
	v_and_b32_e32 v251, 0xffff0000, v244
	v_rcp_f32_e32 v250, v250
	v_rcp_f32_e32 v251, v251
	v_lshlrev_b32_e32 v248, 16, v240
	v_and_b32_e32 v249, 0xffff0000, v240
	v_pk_mul_f32 v[250:251], v[250:251], v[248:249]
	v_pk_mul_f32 v[68:69], v[68:69], v[250:251]
	v_lshlrev_b32_e32 v246, 16, v245
	v_and_b32_e32 v247, 0xffff0000, v245
	v_rcp_f32_e32 v246, v246
	v_rcp_f32_e32 v247, v247
	v_lshlrev_b32_e32 v174, 16, v241
	v_and_b32_e32 v175, 0xffff0000, v241
	v_pk_mul_f32 v[246:247], v[246:247], v[174:175]
	v_pk_mul_f32 v[70:71], v[70:71], v[246:247]
	global_load_dwordx4 v[238:241], v172, s[4:5] offset:256
	global_load_dwordx4 v[242:245], v172, s[4:5] offset:2304
	s_waitcnt vmcnt(14)
	v_lshlrev_b32_e32 v250, 16, v136
	v_and_b32_e32 v251, 0xffff0000, v136
	v_rcp_f32_e32 v250, v250
	v_rcp_f32_e32 v251, v251
	v_lshlrev_b32_e32 v248, 16, v132
	v_and_b32_e32 v249, 0xffff0000, v132
	v_pk_mul_f32 v[250:251], v[250:251], v[248:249]
	v_pk_mul_f32 v[64:65], v[64:65], v[250:251]
	v_lshlrev_b32_e32 v246, 16, v137
	v_and_b32_e32 v247, 0xffff0000, v137
	v_rcp_f32_e32 v246, v246
	v_rcp_f32_e32 v247, v247
	v_lshlrev_b32_e32 v174, 16, v133
	v_and_b32_e32 v175, 0xffff0000, v133
	v_pk_mul_f32 v[246:247], v[246:247], v[174:175]
	v_pk_mul_f32 v[66:67], v[66:67], v[246:247]
	v_lshlrev_b32_e32 v250, 16, v138
	v_and_b32_e32 v251, 0xffff0000, v138
	v_rcp_f32_e32 v250, v250
	v_rcp_f32_e32 v251, v251
	v_lshlrev_b32_e32 v248, 16, v134
	v_and_b32_e32 v249, 0xffff0000, v134
	v_pk_mul_f32 v[250:251], v[250:251], v[248:249]
	v_pk_mul_f32 v[60:61], v[60:61], v[250:251]
	v_lshlrev_b32_e32 v246, 16, v139
	v_and_b32_e32 v247, 0xffff0000, v139
	v_rcp_f32_e32 v246, v246
	v_rcp_f32_e32 v247, v247
	v_lshlrev_b32_e32 v174, 16, v135
	v_and_b32_e32 v175, 0xffff0000, v135
	v_pk_mul_f32 v[246:247], v[246:247], v[174:175]
	v_pk_mul_f32 v[62:63], v[62:63], v[246:247]
	s_waitcnt vmcnt(12)
	v_lshlrev_b32_e32 v250, 16, v194
	v_and_b32_e32 v251, 0xffff0000, v194
	v_rcp_f32_e32 v250, v250
	v_rcp_f32_e32 v251, v251
	v_lshlrev_b32_e32 v248, 16, v190
	v_and_b32_e32 v249, 0xffff0000, v190
	v_pk_mul_f32 v[250:251], v[250:251], v[248:249]
	v_pk_mul_f32 v[56:57], v[56:57], v[250:251]
	v_lshlrev_b32_e32 v246, 16, v195
	v_and_b32_e32 v247, 0xffff0000, v195
	v_rcp_f32_e32 v246, v246
	v_rcp_f32_e32 v247, v247
	v_lshlrev_b32_e32 v174, 16, v191
	v_and_b32_e32 v175, 0xffff0000, v191
	v_pk_mul_f32 v[246:247], v[246:247], v[174:175]
	v_pk_mul_f32 v[58:59], v[58:59], v[246:247]
	v_lshlrev_b32_e32 v250, 16, v196
	v_and_b32_e32 v251, 0xffff0000, v196
	v_rcp_f32_e32 v250, v250
	v_rcp_f32_e32 v251, v251
	v_lshlrev_b32_e32 v248, 16, v192
	v_and_b32_e32 v249, 0xffff0000, v192
	v_pk_mul_f32 v[250:251], v[250:251], v[248:249]
	v_pk_mul_f32 v[52:53], v[52:53], v[250:251]
	v_lshlrev_b32_e32 v246, 16, v197
	v_and_b32_e32 v247, 0xffff0000, v197
	v_rcp_f32_e32 v246, v246
	v_rcp_f32_e32 v247, v247
	v_lshlrev_b32_e32 v174, 16, v193
	v_and_b32_e32 v175, 0xffff0000, v193
	v_pk_mul_f32 v[246:247], v[246:247], v[174:175]
	v_pk_mul_f32 v[54:55], v[54:55], v[246:247]
	s_waitcnt vmcnt(10)
	v_lshlrev_b32_e32 v250, 16, v202
	v_and_b32_e32 v251, 0xffff0000, v202
	v_rcp_f32_e32 v250, v250
	v_rcp_f32_e32 v251, v251
	v_lshlrev_b32_e32 v248, 16, v198
	v_and_b32_e32 v249, 0xffff0000, v198
	v_pk_mul_f32 v[250:251], v[250:251], v[248:249]
	v_pk_mul_f32 v[48:49], v[48:49], v[250:251]
	v_lshlrev_b32_e32 v246, 16, v203
	v_and_b32_e32 v247, 0xffff0000, v203
	v_rcp_f32_e32 v246, v246
	v_rcp_f32_e32 v247, v247
	v_lshlrev_b32_e32 v174, 16, v199
	v_and_b32_e32 v175, 0xffff0000, v199
	v_pk_mul_f32 v[246:247], v[246:247], v[174:175]
	v_pk_mul_f32 v[50:51], v[50:51], v[246:247]
	v_lshlrev_b32_e32 v250, 16, v204
	v_and_b32_e32 v251, 0xffff0000, v204
	v_rcp_f32_e32 v250, v250
	v_rcp_f32_e32 v251, v251
	v_lshlrev_b32_e32 v248, 16, v200
	v_and_b32_e32 v249, 0xffff0000, v200
	v_pk_mul_f32 v[250:251], v[250:251], v[248:249]
	v_pk_mul_f32 v[44:45], v[44:45], v[250:251]
	v_lshlrev_b32_e32 v246, 16, v205
	v_and_b32_e32 v247, 0xffff0000, v205
	v_rcp_f32_e32 v246, v246
	v_rcp_f32_e32 v247, v247
	v_lshlrev_b32_e32 v174, 16, v201
	v_and_b32_e32 v175, 0xffff0000, v201
	v_pk_mul_f32 v[246:247], v[246:247], v[174:175]
	v_pk_mul_f32 v[46:47], v[46:47], v[246:247]
	s_waitcnt vmcnt(8)
	v_lshlrev_b32_e32 v250, 16, v210
	v_and_b32_e32 v251, 0xffff0000, v210
	v_rcp_f32_e32 v250, v250
	v_rcp_f32_e32 v251, v251
	v_lshlrev_b32_e32 v248, 16, v206
	v_and_b32_e32 v249, 0xffff0000, v206
	v_pk_mul_f32 v[250:251], v[250:251], v[248:249]
	v_pk_mul_f32 v[40:41], v[40:41], v[250:251]
	v_lshlrev_b32_e32 v246, 16, v211
	v_and_b32_e32 v247, 0xffff0000, v211
	v_rcp_f32_e32 v246, v246
	v_rcp_f32_e32 v247, v247
	v_lshlrev_b32_e32 v174, 16, v207
	v_and_b32_e32 v175, 0xffff0000, v207
	v_pk_mul_f32 v[246:247], v[246:247], v[174:175]
	v_pk_mul_f32 v[42:43], v[42:43], v[246:247]
	v_lshlrev_b32_e32 v250, 16, v212
	v_and_b32_e32 v251, 0xffff0000, v212
	v_rcp_f32_e32 v250, v250
	v_rcp_f32_e32 v251, v251
	v_lshlrev_b32_e32 v248, 16, v208
	v_and_b32_e32 v249, 0xffff0000, v208
	v_pk_mul_f32 v[250:251], v[250:251], v[248:249]
	v_pk_mul_f32 v[36:37], v[36:37], v[250:251]
	v_lshlrev_b32_e32 v246, 16, v213
	v_and_b32_e32 v247, 0xffff0000, v213
	v_rcp_f32_e32 v246, v246
	v_rcp_f32_e32 v247, v247
	v_lshlrev_b32_e32 v174, 16, v209
	v_and_b32_e32 v175, 0xffff0000, v209
	v_pk_mul_f32 v[246:247], v[246:247], v[174:175]
	v_pk_mul_f32 v[38:39], v[38:39], v[246:247]
	s_waitcnt vmcnt(6)
	v_lshlrev_b32_e32 v250, 16, v218
	v_and_b32_e32 v251, 0xffff0000, v218
	v_rcp_f32_e32 v250, v250
	v_rcp_f32_e32 v251, v251
	v_lshlrev_b32_e32 v248, 16, v214
	v_and_b32_e32 v249, 0xffff0000, v214
	v_pk_mul_f32 v[250:251], v[250:251], v[248:249]
	v_pk_mul_f32 v[32:33], v[32:33], v[250:251]
	v_lshlrev_b32_e32 v246, 16, v219
	v_and_b32_e32 v247, 0xffff0000, v219
	v_rcp_f32_e32 v246, v246
	v_rcp_f32_e32 v247, v247
	v_lshlrev_b32_e32 v174, 16, v215
	v_and_b32_e32 v175, 0xffff0000, v215
	v_pk_mul_f32 v[246:247], v[246:247], v[174:175]
	v_pk_mul_f32 v[34:35], v[34:35], v[246:247]
	v_lshlrev_b32_e32 v250, 16, v220
	v_and_b32_e32 v251, 0xffff0000, v220
	v_rcp_f32_e32 v250, v250
	v_rcp_f32_e32 v251, v251
	v_lshlrev_b32_e32 v248, 16, v216
	v_and_b32_e32 v249, 0xffff0000, v216
	v_pk_mul_f32 v[250:251], v[250:251], v[248:249]
	v_pk_mul_f32 v[28:29], v[28:29], v[250:251]
	v_lshlrev_b32_e32 v246, 16, v221
	v_and_b32_e32 v247, 0xffff0000, v221
	v_rcp_f32_e32 v246, v246
	v_rcp_f32_e32 v247, v247
	v_lshlrev_b32_e32 v174, 16, v217
	v_and_b32_e32 v175, 0xffff0000, v217
	v_pk_mul_f32 v[246:247], v[246:247], v[174:175]
	v_pk_mul_f32 v[30:31], v[30:31], v[246:247]
	s_waitcnt vmcnt(4)
	v_lshlrev_b32_e32 v250, 16, v226
	v_and_b32_e32 v251, 0xffff0000, v226
	v_rcp_f32_e32 v250, v250
	v_rcp_f32_e32 v251, v251
	v_lshlrev_b32_e32 v248, 16, v222
	v_and_b32_e32 v249, 0xffff0000, v222
	v_pk_mul_f32 v[250:251], v[250:251], v[248:249]
	v_pk_mul_f32 v[24:25], v[24:25], v[250:251]
	v_lshlrev_b32_e32 v246, 16, v227
	v_and_b32_e32 v247, 0xffff0000, v227
	v_rcp_f32_e32 v246, v246
	v_rcp_f32_e32 v247, v247
	v_lshlrev_b32_e32 v174, 16, v223
	v_and_b32_e32 v175, 0xffff0000, v223
	v_pk_mul_f32 v[246:247], v[246:247], v[174:175]
	v_pk_mul_f32 v[26:27], v[26:27], v[246:247]
	v_lshlrev_b32_e32 v250, 16, v228
	v_and_b32_e32 v251, 0xffff0000, v228
	v_rcp_f32_e32 v250, v250
	v_rcp_f32_e32 v251, v251
	v_lshlrev_b32_e32 v248, 16, v224
	v_and_b32_e32 v249, 0xffff0000, v224
	v_pk_mul_f32 v[250:251], v[250:251], v[248:249]
	v_pk_mul_f32 v[20:21], v[20:21], v[250:251]
	v_lshlrev_b32_e32 v246, 16, v229
	v_and_b32_e32 v247, 0xffff0000, v229
	v_rcp_f32_e32 v246, v246
	v_rcp_f32_e32 v247, v247
	v_lshlrev_b32_e32 v174, 16, v225
	v_and_b32_e32 v175, 0xffff0000, v225
	v_pk_mul_f32 v[246:247], v[246:247], v[174:175]
	v_pk_mul_f32 v[22:23], v[22:23], v[246:247]
	s_waitcnt vmcnt(2)
	v_lshlrev_b32_e32 v250, 16, v234
	v_and_b32_e32 v251, 0xffff0000, v234
	v_rcp_f32_e32 v250, v250
	v_rcp_f32_e32 v251, v251
	v_lshlrev_b32_e32 v248, 16, v230
	v_and_b32_e32 v249, 0xffff0000, v230
	v_pk_mul_f32 v[250:251], v[250:251], v[248:249]
	v_pk_mul_f32 v[16:17], v[16:17], v[250:251]
	v_lshlrev_b32_e32 v246, 16, v235
	v_and_b32_e32 v247, 0xffff0000, v235
	v_rcp_f32_e32 v246, v246
	v_rcp_f32_e32 v247, v247
	v_lshlrev_b32_e32 v174, 16, v231
	v_and_b32_e32 v175, 0xffff0000, v231
	v_pk_mul_f32 v[246:247], v[246:247], v[174:175]
	v_pk_mul_f32 v[18:19], v[18:19], v[246:247]
	v_lshlrev_b32_e32 v250, 16, v236
	v_and_b32_e32 v251, 0xffff0000, v236
	v_rcp_f32_e32 v250, v250
	v_rcp_f32_e32 v251, v251
	v_lshlrev_b32_e32 v248, 16, v232
	v_and_b32_e32 v249, 0xffff0000, v232
	v_pk_mul_f32 v[250:251], v[250:251], v[248:249]
	v_pk_mul_f32 v[12:13], v[12:13], v[250:251]
	v_lshlrev_b32_e32 v246, 16, v237
	v_and_b32_e32 v247, 0xffff0000, v237
	v_rcp_f32_e32 v246, v246
	v_rcp_f32_e32 v247, v247
	v_lshlrev_b32_e32 v174, 16, v233
	v_and_b32_e32 v175, 0xffff0000, v233
	v_pk_mul_f32 v[246:247], v[246:247], v[174:175]
	v_pk_mul_f32 v[14:15], v[14:15], v[246:247]
	s_waitcnt vmcnt(0)
	v_lshlrev_b32_e32 v250, 16, v242
	v_and_b32_e32 v251, 0xffff0000, v242
	v_rcp_f32_e32 v250, v250
	v_rcp_f32_e32 v251, v251
	v_lshlrev_b32_e32 v248, 16, v238
	v_and_b32_e32 v249, 0xffff0000, v238
	v_pk_mul_f32 v[250:251], v[250:251], v[248:249]
	v_pk_mul_f32 v[8:9], v[8:9], v[250:251]
	v_lshlrev_b32_e32 v246, 16, v243
	v_and_b32_e32 v247, 0xffff0000, v243
	v_rcp_f32_e32 v246, v246
	v_rcp_f32_e32 v247, v247
	v_lshlrev_b32_e32 v174, 16, v239
	v_and_b32_e32 v175, 0xffff0000, v239
	v_pk_mul_f32 v[246:247], v[246:247], v[174:175]
	v_pk_mul_f32 v[10:11], v[10:11], v[246:247]
	v_lshlrev_b32_e32 v250, 16, v244
	v_and_b32_e32 v251, 0xffff0000, v244
	v_rcp_f32_e32 v250, v250
	v_rcp_f32_e32 v251, v251
	v_lshlrev_b32_e32 v248, 16, v240
	v_and_b32_e32 v249, 0xffff0000, v240
	v_pk_mul_f32 v[250:251], v[250:251], v[248:249]
	v_pk_mul_f32 v[4:5], v[4:5], v[250:251]
	v_lshlrev_b32_e32 v246, 16, v245
	v_and_b32_e32 v247, 0xffff0000, v245
	v_rcp_f32_e32 v246, v246
	v_rcp_f32_e32 v247, v247
	v_lshlrev_b32_e32 v174, 16, v241
	v_and_b32_e32 v175, 0xffff0000, v241
	v_pk_mul_f32 v[246:247], v[246:247], v[174:175]
	v_pk_mul_f32 v[6:7], v[6:7], v[246:247]
	v_readfirstlane_b32 s35, v176
	s_nop 3
	s_lshr_b32 s35, s35, 6
	s_cmp_ge_u32 s35, 4
	s_cbranch_scc0 .LBB0_206
	s_setprio 1
	s_branch .LBB0_206
